# v4 + FFT: next-unit input prefetch issued after stage 1 so stage-1 twiddle waits do not drain it; counted vmcnt at commit
# speedup vs baseline: 1.0435x; 1.0025x over previous
.LBB0_545:
	s_waitcnt vmcnt(4)
	ds_write_b128 v198, v[22:25]
	ds_write_b128 v199, v[18:21]
	ds_write_b128 v200, v[62:65]
	ds_write_b128 v201, v[58:61]
	ds_write_b128 v202, v[70:73]
	ds_write_b128 v203, v[66:69]
	ds_write_b128 v204, v[78:81]
	ds_write_b128 v205, v[74:77]
	global_load_dwordx2 v[118:119], v[82:83], off
	global_load_dwordx2 v[112:113], v[82:83], off offset:1024
	global_load_dwordx2 v[116:117], v[82:83], off offset:2048
	global_load_dwordx2 v[114:115], v[82:83], off offset:3072
	s_add_i32 s0, s1, s5
	s_cmpk_gt_i32 s0, 0x2ff
	s_cselect_b64 s[22:23], -1, 0
	s_cmpk_lt_i32 s0, 0x300
	s_cselect_b32 s10, s0, s1
	s_lshl_b32 s20, s10, 6
	s_cmpk_gt_i32 s10, 0x1ff
	s_mov_b64 s[50:51], -1
	s_waitcnt lgkmcnt(0)
	s_barrier
	s_cbranch_scc0 .LBB0_547
	s_add_i32 s1, s20, 0x7fff8000
	s_and_b32 s48, s1, 0x7ffff800
	s_lshl_b32 s1, s10, 3
	s_and_b32 s1, s1, 0xf8
	s_mov_b64 s[50:51], 0

.LBB0_549:
	s_ashr_i32 s49, s48, 31
	s_lshl_b64 s[20:21], s[48:49], 1
	s_add_u32 s20, s42, s20
	s_addc_u32 s21, s43, s21
	v_add3_u32 v20, v20, v145, s1
	v_mov_b64_e32 v[78:79], s[20:21]
	v_mad_i64_i32 v[20:21], s[20:21], v20, s8, v[78:79]
	v_lshlrev_b32_e32 v0, 1, v0
	v_lshl_add_u64 v[20:21], v[20:21], 0, v[0:1]
	v_add3_u32 v0, v19, v149, s1
	v_mad_i64_i32 v[22:23], s[20:21], v0, s8, v[78:79]
	v_lshlrev_b32_e32 v0, 1, v18
	v_lshl_add_u64 v[18:19], v[22:23], 0, v[0:1]
	v_add3_u32 v0, v61, v153, s1
	v_mad_i64_i32 v[62:63], s[20:21], v0, s8, v[78:79]
	v_lshlrev_b32_e32 v0, 1, v60
	v_lshl_add_u64 v[60:61], v[62:63], 0, v[0:1]
	v_add3_u32 v0, v59, v157, s1
	v_mad_i64_i32 v[62:63], s[20:21], v0, s8, v[78:79]
	v_lshlrev_b32_e32 v0, 1, v58
	v_lshl_add_u64 v[58:59], v[62:63], 0, v[0:1]
	v_add3_u32 v0, v69, v161, s1
	v_mad_i64_i32 v[70:71], s[20:21], v0, s8, v[78:79]
	v_lshlrev_b32_e32 v0, 1, v68
	v_lshl_add_u64 v[68:69], v[70:71], 0, v[0:1]
	v_add3_u32 v0, v67, v165, s1
	v_mad_i64_i32 v[70:71], s[20:21], v0, s8, v[78:79]
	v_lshlrev_b32_e32 v0, 1, v66
	v_lshl_add_u64 v[66:67], v[70:71], 0, v[0:1]
	v_add3_u32 v0, v77, v169, s1
	v_mad_i64_i32 v[80:81], s[20:21], v0, s8, v[78:79]
	v_lshlrev_b32_e32 v0, 1, v76
	v_lshl_add_u64 v[76:77], v[80:81], 0, v[0:1]
	v_add3_u32 v0, v75, v173, s1
	v_mad_i64_i32 v[78:79], s[20:21], v0, s8, v[78:79]
	v_lshlrev_b32_e32 v0, 1, v74
	v_mov_b32_e32 v111, v1
	v_lshl_add_u64 v[74:75], v[78:79], 0, v[0:1]
	v_lshl_add_u64 v[20:21], v[20:21], 0, v[110:111]
	v_lshl_add_u64 v[18:19], v[18:19], 0, v[110:111]
	v_lshl_add_u64 v[60:61], v[60:61], 0, v[110:111]
	v_lshl_add_u64 v[58:59], v[58:59], 0, v[110:111]
	v_lshl_add_u64 v[68:69], v[68:69], 0, v[110:111]
	v_lshl_add_u64 v[66:67], v[66:67], 0, v[110:111]
	v_lshl_add_u64 v[76:77], v[76:77], 0, v[110:111]
	v_lshl_add_u64 v[74:75], v[74:75], 0, v[110:111]
	s_mov_b64 s[48:49], -1
	s_and_b64 vcc, exec, s[16:17]
	s_cbranch_vccz .LBB0_553
	global_load_dwordx4 v[82:85], v[92:93], off
	global_load_dwordx4 v[86:89], v[96:97], off
	s_mov_b32 s1, 1
	v_mov_b32_e32 v120, v182
	v_mov_b32_e32 v0, v181
	v_mov_b32_e32 v111, v180
	s_waitcnt vmcnt(5)
	v_mov_b64_e32 v[126:127], v[118:119]
	s_waitcnt vmcnt(4)
	v_mov_b64_e32 v[124:125], v[112:113]
	s_waitcnt vmcnt(3)
	v_mov_b64_e32 v[122:123], v[116:117]
	s_waitcnt vmcnt(2)
	v_mov_b64_e32 v[128:129], v[114:115]

.LBB0_556:
	s_mov_b32 s1, 0
	s_waitcnt lgkmcnt(0)
	s_barrier
	global_load_dwordx4 v[22:25], v[20:21], off
	s_nop 0
	global_load_dwordx4 v[18:21], v[18:19], off
	s_nop 0
	global_load_dwordx4 v[62:65], v[60:61], off
	s_nop 0
	global_load_dwordx4 v[58:61], v[58:59], off
	s_nop 0
	global_load_dwordx4 v[70:73], v[68:69], off
	s_nop 0
	global_load_dwordx4 v[66:69], v[66:67], off
	s_nop 0
	global_load_dwordx4 v[78:81], v[76:77], off
	s_nop 0
	global_load_dwordx4 v[74:77], v[74:75], off
.LBB0_557:
	v_add_u32_e32 v0, s1, v185
	v_add_u32_e32 v82, 0x11000, v0
	v_add_u32_e32 v84, 0x11440, v0
	v_add_u32_e32 v86, 0x19800, v0
	v_add_u32_e32 v88, 0x19c40, v0
	ds_read_b64_tr_b16 v[82:83], v82
	ds_read_b64_tr_b16 v[84:85], v84
	ds_read_b64_tr_b16 v[86:87], v86
	ds_read_b64_tr_b16 v[88:89], v88
	s_waitcnt lgkmcnt(2)
	v_mfma_f32_16x16x32_f16 v[82:85], v[54:57], v[82:85], 0
	s_waitcnt vmcnt(9)
	v_add_u32_e32 v112, 0x13200, v0
	ds_read_b64_tr_b16 v[112:113], v112
	s_waitcnt vmcnt(8)
	v_add_u32_e32 v114, 0x13640, v0
	s_waitcnt lgkmcnt(1)
	v_mfma_f32_16x16x32_f16 v[82:85], v[50:53], v[86:89], v[82:85]
	v_add_u32_e32 v116, 0x1ba00, v0
	v_add_u32_e32 v117, 0x1be40, v0
	ds_read_b64_tr_b16 v[114:115], v114
	ds_read_b64_tr_b16 v[86:87], v116
	ds_read_b64_tr_b16 v[88:89], v117
	s_waitcnt lgkmcnt(2)
	v_mfma_f32_16x16x32_f16 v[82:85], v[46:49], v[112:115], v[82:85]
	v_add_u32_e32 v118, 0x15400, v0
	ds_read_b64_tr_b16 v[112:113], v118
	v_add_u32_e32 v119, 0x15840, v0
	s_waitcnt lgkmcnt(1)
	v_mfma_f32_16x16x32_f16 v[82:85], v[42:45], v[86:89], v[82:85]
	v_add_u32_e32 v120, 0x1dc00, v0
	v_add_u32_e32 v121, 0x1e040, v0
	ds_read_b64_tr_b16 v[114:115], v119
	ds_read_b64_tr_b16 v[86:87], v120
	ds_read_b64_tr_b16 v[88:89], v121
	s_waitcnt lgkmcnt(2)
	v_mfma_f32_16x16x32_f16 v[82:85], v[38:41], v[112:115], v[82:85]
	v_add_u32_e32 v122, 0x17600, v0
	ds_read_b64_tr_b16 v[112:113], v122
	v_add_u32_e32 v123, 0x17a40, v0
	s_waitcnt lgkmcnt(1)
	v_mfma_f32_16x16x32_f16 v[82:85], v[34:37], v[86:89], v[82:85]
	v_add_u32_e32 v124, 0x1fe00, v0
	v_add_u32_e32 v125, 0x20240, v0
	ds_read_b64_tr_b16 v[114:115], v123
	ds_read_b64_tr_b16 v[86:87], v124
	ds_read_b64_tr_b16 v[88:89], v125
	s_waitcnt lgkmcnt(2)
	v_mfma_f32_16x16x32_f16 v[82:85], v[30:33], v[112:115], v[82:85]
	v_add_u32_e32 v111, s1, v193
	v_add_u32_e32 v126, 0x11020, v0
	v_add_u32_e32 v127, 0x11460, v0
	s_waitcnt lgkmcnt(0)
	v_mfma_f32_16x16x32_f16 v[82:85], v[26:29], v[86:89], v[82:85]
	v_add_u32_e32 v128, 0x19820, v0
	v_add_u32_e32 v116, 0x19c60, v0
	v_add_u32_e32 v117, 0x13220, v0
	v_add_u32_e32 v118, 0x13660, v0
	v_add_u32_e32 v119, 0x1ba20, v0
	s_nop 2
	v_cvt_f16_f32_e32 v82, v82
	v_cvt_f16_f32_e32 v83, v83
	v_cvt_f16_f32_e32 v84, v84
	v_cvt_f16_f32_e32 v85, v85
	ds_write_b16 v111, v82
	ds_write_b16 v111, v83 offset:256
	ds_write_b16 v111, v84 offset:512
	ds_write_b16 v111, v85 offset:768
	ds_read_b64_tr_b16 v[82:83], v126
	ds_read_b64_tr_b16 v[84:85], v127
	ds_read_b64_tr_b16 v[86:87], v128
	ds_read_b64_tr_b16 v[88:89], v116
	s_waitcnt lgkmcnt(2)
	v_mfma_f32_16x16x32_f16 v[82:85], v[54:57], v[82:85], 0
	ds_read_b64_tr_b16 v[112:113], v117
	v_add_u32_e32 v120, 0x1be60, v0
	v_add_u32_e32 v121, 0x15420, v0
	s_waitcnt lgkmcnt(1)
	v_mfma_f32_16x16x32_f16 v[82:85], v[50:53], v[86:89], v[82:85]
	ds_read_b64_tr_b16 v[114:115], v118
	ds_read_b64_tr_b16 v[86:87], v119
	ds_read_b64_tr_b16 v[88:89], v120
	v_add_u32_e32 v122, 0x15860, v0
	v_add_u32_e32 v116, 0x1dc20, v0
	s_waitcnt lgkmcnt(2)
	v_mfma_f32_16x16x32_f16 v[82:85], v[46:49], v[112:115], v[82:85]
	ds_read_b64_tr_b16 v[112:113], v121
	v_add_u32_e32 v123, 0x1e060, v0
	v_add_u32_e32 v117, 0x17620, v0
	s_waitcnt lgkmcnt(1)
	v_mfma_f32_16x16x32_f16 v[82:85], v[42:45], v[86:89], v[82:85]
	ds_read_b64_tr_b16 v[114:115], v122
	ds_read_b64_tr_b16 v[86:87], v116
	ds_read_b64_tr_b16 v[88:89], v123
	v_add_u32_e32 v118, 0x17a60, v0
	v_add_u32_e32 v116, 0x1fe20, v0
	s_waitcnt lgkmcnt(2)
	v_mfma_f32_16x16x32_f16 v[82:85], v[38:41], v[112:115], v[82:85]
	ds_read_b64_tr_b16 v[112:113], v117
	v_add_u32_e32 v0, 0x20260, v0
	s_add_i32 s1, s1, 64
	s_waitcnt lgkmcnt(1)
	v_mfma_f32_16x16x32_f16 v[82:85], v[34:37], v[86:89], v[82:85]
	ds_read_b64_tr_b16 v[114:115], v118
	ds_read_b64_tr_b16 v[86:87], v116
	ds_read_b64_tr_b16 v[88:89], v0
	s_cmpk_eq_i32 s1, 0x100
	s_waitcnt lgkmcnt(2)
	v_mfma_f32_16x16x32_f16 v[82:85], v[30:33], v[112:115], v[82:85]
	s_waitcnt lgkmcnt(0)
	v_mfma_f32_16x16x32_f16 v[82:85], v[26:29], v[86:89], v[82:85]
	s_nop 7
	v_cvt_f16_f32_e32 v0, v82
	v_cvt_f16_f32_e32 v82, v83
	v_cvt_f16_f32_e32 v83, v84
	v_cvt_f16_f32_e32 v84, v85
	ds_write_b16 v111, v0 offset:32
	ds_write_b16 v111, v82 offset:288
	ds_write_b16 v111, v83 offset:544
	ds_write_b16 v111, v84 offset:800
	s_cbranch_scc0 .LBB0_557
	s_ashr_i32 s39, s38, 31
	s_mul_i32 s26, s19, 0xc000
	s_lshl_b64 s[20:21], s[38:39], 1
	s_lshl_b64 s[24:25], s[26:27], 1
	s_add_u32 s1, s42, s24
	s_addc_u32 s10, s43, s25
	s_add_u32 s48, s1, s20
	v_lshl_add_u64 v[82:83], v[98:99], 0, s[20:21]
	s_addc_u32 s49, s10, s21
	s_mov_b64 s[38:39], -1
	s_and_b64 vcc, exec, s[16:17]
	s_waitcnt lgkmcnt(0)
	s_barrier
	s_cbranch_vccz .LBB0_560
	ds_read_b128 v[84:87], v206
	v_add_u32_e32 v0, s19, v176
	v_mad_i64_i32 v[88:89], s[20:21], v0, s8, v[82:83]
	s_mov_b64 s[38:39], 0
	s_waitcnt lgkmcnt(0)
	global_store_dwordx4 v[88:89], v[84:87], off
